# GEMM first half-steps: fragment reads first, LDS-DMA pieces spread through the MFMA block instead of in front of it (all five loops)
# speedup vs baseline: 1.0402x; 1.0132x over previous
.LBB0_125:
	s_waitcnt lgkmcnt(0)
	s_cmpk_gt_u32 s17, 0x54
	s_cselect_b64 s[24:25], -1, 0
	s_and_b64 vcc, exec, s[24:25]
	s_barrier
	s_and_b32 s19, s17, 2
	s_mulk_i32 s19, 0x6000
	v_add_u32_e32 v110, s19, v142
	ds_read_b128 v[106:109], v110
	ds_read_b128 v[144:147], v110 offset:1024
	s_cbranch_vccnz .Lgm_G5x_nodma0
	s_and_b32 s89, s8, 3
	s_mulk_i32 s89, 0x6000
	s_add_i32 s89, s89, s88
	s_mov_b32 m0, s89
	v_mfma_f32_16x16x32_bf16 v[102:105], v[2:5], v[26:29], v[102:105]
	v_mfma_f32_16x16x32_bf16 v[98:101], v[6:9], v[26:29], v[98:101]
	global_load_lds_dwordx4 v126, s[90:91]
	s_add_i32 m0, s89, 0x2000
	v_mfma_f32_16x16x32_bf16 v[86:89], v[10:13], v[26:29], v[86:89]
	v_mfma_f32_16x16x32_bf16 v[70:73], v[14:17], v[26:29], v[70:73]
	global_load_lds_dwordx4 v128, s[90:91]
	s_add_i32 m0, s89, 0x4000
	v_mfma_f32_16x16x32_bf16 v[90:93], v[2:5], v[22:25], v[90:93]
	v_mfma_f32_16x16x32_bf16 v[78:81], v[6:9], v[22:25], v[78:81]
	global_load_lds_dwordx4 v130, s[92:93]
	v_mfma_f32_16x16x32_bf16 v[62:65], v[10:13], v[22:25], v[62:65]
	v_mfma_f32_16x16x32_bf16 v[50:53], v[14:17], v[22:25], v[50:53]
	s_add_u32 s90, s90, 64
	s_addc_u32 s91, s91, 0
	s_add_u32 s92, s92, 64
	s_addc_u32 s93, s93, 0
.LBB0_127:
	s_waitcnt lgkmcnt(0)
	s_barrier
	v_mfma_f32_16x16x32_bf16 v[74:77], v[2:5], v[106:109], v[74:77]
	v_mfma_f32_16x16x32_bf16 v[58:61], v[6:9], v[106:109], v[58:61]
	v_mfma_f32_16x16x32_bf16 v[38:41], v[10:13], v[106:109], v[38:41]
	v_mfma_f32_16x16x32_bf16 v[30:33], v[14:17], v[106:109], v[30:33]
	s_add_i32 s26, s8, -2
	s_and_b32 s28, s26, 3
	s_mulk_i32 s28, 0x6000
	v_add_u32_e32 v22, s28, v140
	ds_read_b128 v[118:121], v22
	ds_read_b128 v[114:117], v22 offset:1024
	ds_read_b128 v[110:113], v22 offset:2048
	ds_read_b128 v[106:109], v22 offset:3072
	v_add_u32_e32 v143, s28, v141
	ds_read_b128 v[26:29], v143
	ds_read_b128 v[22:25], v143 offset:1024
	v_mfma_f32_16x16x32_bf16 v[94:97], v[2:5], v[144:147], v[94:97]
	v_mfma_f32_16x16x32_bf16 v[82:85], v[6:9], v[144:147], v[82:85]
	v_mfma_f32_16x16x32_bf16 v[66:69], v[10:13], v[144:147], v[66:69]
	v_mfma_f32_16x16x32_bf16 v[34:37], v[14:17], v[144:147], v[34:37]
	s_mov_b64 s[26:27], -1
	s_and_b64 vcc, exec, s[24:25]
	s_cbranch_vccz .LBB0_129
	s_waitcnt vmcnt(0)
	s_mov_b64 s[26:27], 0

.LBB0_131:
	s_waitcnt lgkmcnt(0)
	s_barrier
	v_add_u32_e32 v132, s28, v142
	ds_read_b128 v[144:147], v132
	ds_read_b128 v[122:125], v132 offset:1024
	s_cmpk_gt_u32 s17, 0x53
	s_cbranch_scc1 .Lgm_G5x_nodma1
	s_add_i32 s89, s19, s88
	s_mov_b32 m0, s89
	v_mfma_f32_16x16x32_bf16 v[102:105], v[118:121], v[26:29], v[102:105]
	v_mfma_f32_16x16x32_bf16 v[98:101], v[114:117], v[26:29], v[98:101]
	global_load_lds_dwordx4 v126, s[90:91]
	s_add_i32 m0, s89, 0x2000
	v_mfma_f32_16x16x32_bf16 v[86:89], v[110:113], v[26:29], v[86:89]
	v_mfma_f32_16x16x32_bf16 v[70:73], v[106:109], v[26:29], v[70:73]
	global_load_lds_dwordx4 v128, s[90:91]
	s_add_i32 m0, s89, 0x4000
	v_mfma_f32_16x16x32_bf16 v[90:93], v[118:121], v[22:25], v[90:93]
	v_mfma_f32_16x16x32_bf16 v[78:81], v[114:117], v[22:25], v[78:81]
	global_load_lds_dwordx4 v130, s[92:93]
	v_mfma_f32_16x16x32_bf16 v[62:65], v[110:113], v[22:25], v[62:65]
	v_mfma_f32_16x16x32_bf16 v[50:53], v[106:109], v[22:25], v[50:53]
	s_add_u32 s90, s90, 64
	s_addc_u32 s91, s91, 0
	s_add_u32 s92, s92, 64
	s_addc_u32 s93, s93, 0
.LBB0_133:
	s_waitcnt lgkmcnt(0)
	s_barrier
	v_mfma_f32_16x16x32_bf16 v[74:77], v[118:121], v[144:147], v[74:77]
	v_mfma_f32_16x16x32_bf16 v[58:61], v[114:117], v[144:147], v[58:61]
	v_mfma_f32_16x16x32_bf16 v[38:41], v[110:113], v[144:147], v[38:41]
	v_mfma_f32_16x16x32_bf16 v[30:33], v[106:109], v[144:147], v[30:33]
	s_andn2_b64 vcc, exec, s[22:23]
	s_cbranch_vccnz .LBB0_120
	s_add_i32 s19, s8, -1
	s_and_b32 s19, s19, 2
	s_mulk_i32 s19, 0x6000
	v_add_u32_e32 v22, s19, v140
	ds_read_b128 v[2:5], v22
	ds_read_b128 v[6:9], v22 offset:1024
	ds_read_b128 v[10:13], v22 offset:2048
	ds_read_b128 v[14:17], v22 offset:3072
	v_add_u32_e32 v132, s19, v141
	ds_read_b128 v[26:29], v132
	ds_read_b128 v[22:25], v132 offset:1024
	s_branch .LBB0_120
.Lgm_G5x_nodma1:
	v_mfma_f32_16x16x32_bf16 v[102:105], v[118:121], v[26:29], v[102:105]
	v_mfma_f32_16x16x32_bf16 v[98:101], v[114:117], v[26:29], v[98:101]
	v_mfma_f32_16x16x32_bf16 v[86:89], v[110:113], v[26:29], v[86:89]
	v_mfma_f32_16x16x32_bf16 v[70:73], v[106:109], v[26:29], v[70:73]
	v_mfma_f32_16x16x32_bf16 v[90:93], v[118:121], v[22:25], v[90:93]
	v_mfma_f32_16x16x32_bf16 v[78:81], v[114:117], v[22:25], v[78:81]
	v_mfma_f32_16x16x32_bf16 v[62:65], v[110:113], v[22:25], v[62:65]
	v_mfma_f32_16x16x32_bf16 v[50:53], v[106:109], v[22:25], v[50:53]
	s_branch .LBB0_133
.Lgm_G5x_nodma0:
	v_mfma_f32_16x16x32_bf16 v[102:105], v[2:5], v[26:29], v[102:105]
	v_mfma_f32_16x16x32_bf16 v[98:101], v[6:9], v[26:29], v[98:101]
	v_mfma_f32_16x16x32_bf16 v[86:89], v[10:13], v[26:29], v[86:89]
	v_mfma_f32_16x16x32_bf16 v[70:73], v[14:17], v[26:29], v[70:73]
	v_mfma_f32_16x16x32_bf16 v[90:93], v[2:5], v[22:25], v[90:93]
	v_mfma_f32_16x16x32_bf16 v[78:81], v[6:9], v[22:25], v[78:81]
	v_mfma_f32_16x16x32_bf16 v[62:65], v[10:13], v[22:25], v[62:65]
	v_mfma_f32_16x16x32_bf16 v[50:53], v[14:17], v[22:25], v[50:53]
	s_branch .LBB0_127

.LBB0_187:
	s_waitcnt lgkmcnt(0)
	s_cmp_gt_u32 s19, 28
	s_cselect_b64 s[26:27], -1, 0
	s_and_b64 vcc, exec, s[26:27]
	s_barrier
	s_add_i32 s28, s31, 0xfffe8000
	s_and_b32 s34, s28, 0x10000
	v_add_u32_e32 v170, s34, v230
	ds_read_b128 v[162:165], v170
	ds_read_b128 v[166:169], v170 offset:1024
	ds_read_b128 v[232:235], v170 offset:2048
	ds_read_b128 v[236:239], v170 offset:3072
	s_cbranch_vccnz .Lgm_G4x_nodma0
	s_and_b32 s89, s31, 0x18000
	s_add_i32 s89, s89, s88
	s_mov_b32 m0, s89
	v_mfma_f32_16x16x32_bf16 v[158:161], v[122:125], v[150:153], v[158:161]
	v_mfma_f32_16x16x32_bf16 v[94:97], v[126:129], v[150:153], v[94:97]
	v_mfma_f32_16x16x32_bf16 v[62:65], v[130:133], v[150:153], v[62:65]
	global_load_lds_dwordx4 v186, s[90:91]
	s_add_i32 m0, s89, 0x2000
	v_mfma_f32_16x16x32_bf16 v[30:33], v[134:137], v[150:153], v[30:33]
	v_mfma_f32_16x16x32_bf16 v[118:121], v[122:125], v[146:149], v[118:121]
	v_mfma_f32_16x16x32_bf16 v[86:89], v[126:129], v[146:149], v[86:89]
	global_load_lds_dwordx4 v188, s[90:91]
	s_add_i32 m0, s89, 0x4000
	v_mfma_f32_16x16x32_bf16 v[54:57], v[130:133], v[146:149], v[54:57]
	v_mfma_f32_16x16x32_bf16 v[22:25], v[134:137], v[146:149], v[22:25]
	v_mfma_f32_16x16x32_bf16 v[110:113], v[122:125], v[142:145], v[110:113]
	global_load_lds_dwordx4 v190, s[92:93]
	s_add_i32 m0, s89, 0x6000
	v_mfma_f32_16x16x32_bf16 v[78:81], v[126:129], v[142:145], v[78:81]
	v_mfma_f32_16x16x32_bf16 v[46:49], v[130:133], v[142:145], v[46:49]
	v_mfma_f32_16x16x32_bf16 v[14:17], v[134:137], v[142:145], v[14:17]
	global_load_lds_dwordx4 v192, s[92:93]
	v_mfma_f32_16x16x32_bf16 v[102:105], v[122:125], v[138:141], v[102:105]
	v_mfma_f32_16x16x32_bf16 v[70:73], v[126:129], v[138:141], v[70:73]
	v_mfma_f32_16x16x32_bf16 v[38:41], v[130:133], v[138:141], v[38:41]
	v_mfma_f32_16x16x32_bf16 v[6:9], v[134:137], v[138:141], v[6:9]
	s_add_u32 s90, s90, 64
	s_addc_u32 s91, s91, 0
	s_add_u32 s92, s92, 64
	s_addc_u32 s93, s93, 0
.LBB0_189:
	s_waitcnt lgkmcnt(0)
	s_barrier
	v_mfma_f32_16x16x32_bf16 v[154:157], v[122:125], v[162:165], v[154:157]
	v_mfma_f32_16x16x32_bf16 v[90:93], v[126:129], v[162:165], v[90:93]
	v_mfma_f32_16x16x32_bf16 v[58:61], v[130:133], v[162:165], v[58:61]
	v_mfma_f32_16x16x32_bf16 v[26:29], v[134:137], v[162:165], v[26:29]
	v_mfma_f32_16x16x32_bf16 v[114:117], v[122:125], v[166:169], v[114:117]
	v_mfma_f32_16x16x32_bf16 v[82:85], v[126:129], v[166:169], v[82:85]
	v_mfma_f32_16x16x32_bf16 v[50:53], v[130:133], v[166:169], v[50:53]
	v_mfma_f32_16x16x32_bf16 v[18:21], v[134:137], v[166:169], v[18:21]
	s_add_i32 s28, s31, 0xffff0000
	s_and_b32 s35, s28, 0x18000
	v_add_u32_e32 v138, s35, v200
	ds_read_b128 v[174:177], v138
	ds_read_b128 v[170:173], v138 offset:1024
	ds_read_b128 v[166:169], v138 offset:2048
	ds_read_b128 v[162:165], v138 offset:3072
	v_add_u32_e32 v226, s35, v201
	ds_read_b128 v[150:153], v226
	ds_read_b128 v[146:149], v226 offset:1024
	ds_read_b128 v[142:145], v226 offset:2048
	ds_read_b128 v[138:141], v226 offset:3072
	v_mfma_f32_16x16x32_bf16 v[106:109], v[122:125], v[232:235], v[106:109]
	v_mfma_f32_16x16x32_bf16 v[74:77], v[126:129], v[232:235], v[74:77]
	v_mfma_f32_16x16x32_bf16 v[42:45], v[130:133], v[232:235], v[42:45]
	v_mfma_f32_16x16x32_bf16 v[10:13], v[134:137], v[232:235], v[10:13]
	v_mfma_f32_16x16x32_bf16 v[98:101], v[122:125], v[236:239], v[98:101]
	v_mfma_f32_16x16x32_bf16 v[66:69], v[126:129], v[236:239], v[66:69]
	v_mfma_f32_16x16x32_bf16 v[34:37], v[130:133], v[236:239], v[34:37]
	v_mfma_f32_16x16x32_bf16 v[2:5], v[134:137], v[236:239], v[2:5]
	s_mov_b64 s[28:29], -1
	s_and_b64 vcc, exec, s[26:27]
	s_cbranch_vccz .LBB0_191
	s_waitcnt vmcnt(0)
	s_mov_b64 s[28:29], 0

.LBB0_193:
	s_waitcnt lgkmcnt(0)
	s_barrier
	v_add_u32_e32 v226, s35, v230
	ds_read_b128 v[232:235], v226
	ds_read_b128 v[236:239], v226 offset:1024
	ds_read_b128 v[182:185], v226 offset:2048
	ds_read_b128 v[178:181], v226 offset:3072
	s_cmp_gt_u32 s19, 27
	s_cbranch_scc1 .Lgm_G4x_nodma1
	s_add_i32 s89, s34, s88
	s_mov_b32 m0, s89
	v_mfma_f32_16x16x32_bf16 v[158:161], v[174:177], v[150:153], v[158:161]
	v_mfma_f32_16x16x32_bf16 v[94:97], v[170:173], v[150:153], v[94:97]
	v_mfma_f32_16x16x32_bf16 v[62:65], v[166:169], v[150:153], v[62:65]
	global_load_lds_dwordx4 v186, s[90:91]
	s_add_i32 m0, s89, 0x2000
	v_mfma_f32_16x16x32_bf16 v[30:33], v[162:165], v[150:153], v[30:33]
	v_mfma_f32_16x16x32_bf16 v[118:121], v[174:177], v[146:149], v[118:121]
	v_mfma_f32_16x16x32_bf16 v[86:89], v[170:173], v[146:149], v[86:89]
	global_load_lds_dwordx4 v188, s[90:91]
	s_add_i32 m0, s89, 0x4000
	v_mfma_f32_16x16x32_bf16 v[54:57], v[166:169], v[146:149], v[54:57]
	v_mfma_f32_16x16x32_bf16 v[22:25], v[162:165], v[146:149], v[22:25]
	v_mfma_f32_16x16x32_bf16 v[110:113], v[174:177], v[142:145], v[110:113]
	global_load_lds_dwordx4 v190, s[92:93]
	s_add_i32 m0, s89, 0x6000
	v_mfma_f32_16x16x32_bf16 v[78:81], v[170:173], v[142:145], v[78:81]
	v_mfma_f32_16x16x32_bf16 v[46:49], v[166:169], v[142:145], v[46:49]
	v_mfma_f32_16x16x32_bf16 v[14:17], v[162:165], v[142:145], v[14:17]
	global_load_lds_dwordx4 v192, s[92:93]
	v_mfma_f32_16x16x32_bf16 v[102:105], v[174:177], v[138:141], v[102:105]
	v_mfma_f32_16x16x32_bf16 v[70:73], v[170:173], v[138:141], v[70:73]
	v_mfma_f32_16x16x32_bf16 v[38:41], v[166:169], v[138:141], v[38:41]
	v_mfma_f32_16x16x32_bf16 v[6:9], v[162:165], v[138:141], v[6:9]
	s_add_u32 s90, s90, 64
	s_addc_u32 s91, s91, 0
	s_add_u32 s92, s92, 64
	s_addc_u32 s93, s93, 0
.LBB0_195:
	s_waitcnt lgkmcnt(0)
	s_barrier
	v_mfma_f32_16x16x32_bf16 v[154:157], v[174:177], v[232:235], v[154:157]
	v_mfma_f32_16x16x32_bf16 v[90:93], v[170:173], v[232:235], v[90:93]
	v_mfma_f32_16x16x32_bf16 v[58:61], v[166:169], v[232:235], v[58:61]
	v_mfma_f32_16x16x32_bf16 v[26:29], v[162:165], v[232:235], v[26:29]
	v_mfma_f32_16x16x32_bf16 v[114:117], v[174:177], v[236:239], v[114:117]
	v_mfma_f32_16x16x32_bf16 v[82:85], v[170:173], v[236:239], v[82:85]
	v_mfma_f32_16x16x32_bf16 v[50:53], v[166:169], v[236:239], v[50:53]
	v_mfma_f32_16x16x32_bf16 v[18:21], v[162:165], v[236:239], v[18:21]
	s_andn2_b64 vcc, exec, s[24:25]
	s_cbranch_vccnz .LBB0_182
	s_add_i32 s24, s31, 0xffff8000
	s_and_b32 s24, s24, 0x10000
	v_add_u32_e32 v138, s24, v200
	ds_read_b128 v[122:125], v138
	ds_read_b128 v[126:129], v138 offset:1024
	ds_read_b128 v[130:133], v138 offset:2048
	ds_read_b128 v[134:137], v138 offset:3072
	v_add_u32_e32 v226, s24, v201
	ds_read_b128 v[150:153], v226
	ds_read_b128 v[146:149], v226 offset:1024
	ds_read_b128 v[142:145], v226 offset:2048
	ds_read_b128 v[138:141], v226 offset:3072
	s_branch .LBB0_182
.Lgm_G4x_nodma1:
	v_mfma_f32_16x16x32_bf16 v[158:161], v[174:177], v[150:153], v[158:161]
	v_mfma_f32_16x16x32_bf16 v[94:97], v[170:173], v[150:153], v[94:97]
	v_mfma_f32_16x16x32_bf16 v[62:65], v[166:169], v[150:153], v[62:65]
	v_mfma_f32_16x16x32_bf16 v[30:33], v[162:165], v[150:153], v[30:33]
	v_mfma_f32_16x16x32_bf16 v[118:121], v[174:177], v[146:149], v[118:121]
	v_mfma_f32_16x16x32_bf16 v[86:89], v[170:173], v[146:149], v[86:89]
	v_mfma_f32_16x16x32_bf16 v[54:57], v[166:169], v[146:149], v[54:57]
	v_mfma_f32_16x16x32_bf16 v[22:25], v[162:165], v[146:149], v[22:25]
	v_mfma_f32_16x16x32_bf16 v[110:113], v[174:177], v[142:145], v[110:113]
	v_mfma_f32_16x16x32_bf16 v[78:81], v[170:173], v[142:145], v[78:81]
	v_mfma_f32_16x16x32_bf16 v[46:49], v[166:169], v[142:145], v[46:49]
	v_mfma_f32_16x16x32_bf16 v[14:17], v[162:165], v[142:145], v[14:17]
	v_mfma_f32_16x16x32_bf16 v[102:105], v[174:177], v[138:141], v[102:105]
	v_mfma_f32_16x16x32_bf16 v[70:73], v[170:173], v[138:141], v[70:73]
	v_mfma_f32_16x16x32_bf16 v[38:41], v[166:169], v[138:141], v[38:41]
	v_mfma_f32_16x16x32_bf16 v[6:9], v[162:165], v[138:141], v[6:9]
	s_branch .LBB0_195
.Lgm_G4x_nodma0:
	v_mfma_f32_16x16x32_bf16 v[158:161], v[122:125], v[150:153], v[158:161]
	v_mfma_f32_16x16x32_bf16 v[94:97], v[126:129], v[150:153], v[94:97]
	v_mfma_f32_16x16x32_bf16 v[62:65], v[130:133], v[150:153], v[62:65]
	v_mfma_f32_16x16x32_bf16 v[30:33], v[134:137], v[150:153], v[30:33]
	v_mfma_f32_16x16x32_bf16 v[118:121], v[122:125], v[146:149], v[118:121]
	v_mfma_f32_16x16x32_bf16 v[86:89], v[126:129], v[146:149], v[86:89]
	v_mfma_f32_16x16x32_bf16 v[54:57], v[130:133], v[146:149], v[54:57]
	v_mfma_f32_16x16x32_bf16 v[22:25], v[134:137], v[146:149], v[22:25]
	v_mfma_f32_16x16x32_bf16 v[110:113], v[122:125], v[142:145], v[110:113]
	v_mfma_f32_16x16x32_bf16 v[78:81], v[126:129], v[142:145], v[78:81]
	v_mfma_f32_16x16x32_bf16 v[46:49], v[130:133], v[142:145], v[46:49]
	v_mfma_f32_16x16x32_bf16 v[14:17], v[134:137], v[142:145], v[14:17]
	v_mfma_f32_16x16x32_bf16 v[102:105], v[122:125], v[138:141], v[102:105]
	v_mfma_f32_16x16x32_bf16 v[70:73], v[126:129], v[138:141], v[70:73]
	v_mfma_f32_16x16x32_bf16 v[38:41], v[130:133], v[138:141], v[38:41]
	v_mfma_f32_16x16x32_bf16 v[6:9], v[134:137], v[138:141], v[6:9]
	s_branch .LBB0_189

.LBB0_295:
	s_waitcnt lgkmcnt(0)
	s_cmp_gt_u32 s17, 28
	s_cselect_b64 s[24:25], -1, 0
	s_and_b64 vcc, exec, s[24:25]
	s_barrier
	s_and_b32 s19, s17, 2
	s_mulk_i32 s19, 0x6000
	v_add_u32_e32 v110, s19, v142
	ds_read_b128 v[106:109], v110
	ds_read_b128 v[144:147], v110 offset:1024
	s_cbranch_vccnz .Lgm_G3x_nodma0
	s_and_b32 s69, s8, 3
	s_mulk_i32 s69, 0x6000
	s_add_i32 s69, s69, s29
	s_mov_b32 m0, s69
	v_mfma_f32_16x16x32_bf16 v[102:105], v[2:5], v[26:29], v[102:105]
	v_mfma_f32_16x16x32_bf16 v[98:101], v[6:9], v[26:29], v[98:101]
	global_load_lds_dwordx4 v126, s[44:45]
	s_add_i32 m0, s69, 0x2000
	v_mfma_f32_16x16x32_bf16 v[86:89], v[10:13], v[26:29], v[86:89]
	v_mfma_f32_16x16x32_bf16 v[70:73], v[14:17], v[26:29], v[70:73]
	global_load_lds_dwordx4 v128, s[44:45]
	s_add_i32 m0, s69, 0x4000
	v_mfma_f32_16x16x32_bf16 v[90:93], v[2:5], v[22:25], v[90:93]
	v_mfma_f32_16x16x32_bf16 v[78:81], v[6:9], v[22:25], v[78:81]
	global_load_lds_dwordx4 v130, s[30:31]
	v_mfma_f32_16x16x32_bf16 v[62:65], v[10:13], v[22:25], v[62:65]
	v_mfma_f32_16x16x32_bf16 v[46:49], v[14:17], v[22:25], v[46:49]
	s_add_u32 s44, s44, 64
	s_addc_u32 s45, s45, 0
	s_add_u32 s30, s30, 64
	s_addc_u32 s31, s31, 0

.LBB0_301:
	s_waitcnt lgkmcnt(0)
	s_barrier
	v_add_u32_e32 v132, s28, v142
	ds_read_b128 v[144:147], v132
	ds_read_b128 v[122:125], v132 offset:1024
	s_cmp_gt_u32 s17, 27
	s_cbranch_scc1 .Lgm_G3x_nodma1
	s_add_i32 s69, s19, s29
	s_mov_b32 m0, s69
	v_mfma_f32_16x16x32_bf16 v[102:105], v[118:121], v[26:29], v[102:105]
	v_mfma_f32_16x16x32_bf16 v[98:101], v[114:117], v[26:29], v[98:101]
	global_load_lds_dwordx4 v126, s[44:45]
	s_add_i32 m0, s69, 0x2000
	v_mfma_f32_16x16x32_bf16 v[86:89], v[110:113], v[26:29], v[86:89]
	v_mfma_f32_16x16x32_bf16 v[70:73], v[106:109], v[26:29], v[70:73]
	global_load_lds_dwordx4 v128, s[44:45]
	s_add_i32 m0, s69, 0x4000
	v_mfma_f32_16x16x32_bf16 v[90:93], v[118:121], v[22:25], v[90:93]
	v_mfma_f32_16x16x32_bf16 v[78:81], v[114:117], v[22:25], v[78:81]
	global_load_lds_dwordx4 v130, s[30:31]
	v_mfma_f32_16x16x32_bf16 v[62:65], v[110:113], v[22:25], v[62:65]
	v_mfma_f32_16x16x32_bf16 v[46:49], v[106:109], v[22:25], v[46:49]
	s_add_u32 s44, s44, 64
	s_addc_u32 s45, s45, 0
	s_add_u32 s30, s30, 64
	s_addc_u32 s31, s31, 0

.Lgm_G3x_nodma1:
	v_mfma_f32_16x16x32_bf16 v[102:105], v[118:121], v[26:29], v[102:105]
	v_mfma_f32_16x16x32_bf16 v[98:101], v[114:117], v[26:29], v[98:101]
	v_mfma_f32_16x16x32_bf16 v[86:89], v[110:113], v[26:29], v[86:89]
	v_mfma_f32_16x16x32_bf16 v[70:73], v[106:109], v[26:29], v[70:73]
	v_mfma_f32_16x16x32_bf16 v[90:93], v[118:121], v[22:25], v[90:93]
	v_mfma_f32_16x16x32_bf16 v[78:81], v[114:117], v[22:25], v[78:81]
	v_mfma_f32_16x16x32_bf16 v[62:65], v[110:113], v[22:25], v[62:65]
	v_mfma_f32_16x16x32_bf16 v[46:49], v[106:109], v[22:25], v[46:49]
	s_branch .LBB0_303
.Lgm_G3x_nodma0:
	v_mfma_f32_16x16x32_bf16 v[102:105], v[2:5], v[26:29], v[102:105]
	v_mfma_f32_16x16x32_bf16 v[98:101], v[6:9], v[26:29], v[98:101]
	v_mfma_f32_16x16x32_bf16 v[86:89], v[10:13], v[26:29], v[86:89]
	v_mfma_f32_16x16x32_bf16 v[70:73], v[14:17], v[26:29], v[70:73]
	v_mfma_f32_16x16x32_bf16 v[90:93], v[2:5], v[22:25], v[90:93]
	v_mfma_f32_16x16x32_bf16 v[78:81], v[6:9], v[22:25], v[78:81]
	v_mfma_f32_16x16x32_bf16 v[62:65], v[10:13], v[22:25], v[62:65]
	v_mfma_f32_16x16x32_bf16 v[46:49], v[14:17], v[22:25], v[46:49]
	s_branch .LBB0_297

.LBB0_413:
	s_waitcnt lgkmcnt(0)
	s_cmp_gt_u32 s17, 44
	s_cselect_b64 s[24:25], -1, 0
	s_and_b64 vcc, exec, s[24:25]
	s_barrier
	s_and_b32 s28, s17, 2
	s_mulk_i32 s28, 0x6000
	v_add_u32_e32 v110, s28, v237
	ds_read_b128 v[106:109], v110
	ds_read_b128 v[242:245], v110 offset:1024
	s_cbranch_vccnz .Lgm_G2x_nodma0
	s_and_b32 s89, s8, 3
	s_mulk_i32 s89, 0x6000
	s_add_i32 s89, s89, s88
	s_mov_b32 m0, s89
	v_mfma_f32_16x16x32_bf16 v[102:105], v[14:17], v[26:29], v[102:105]
	v_mfma_f32_16x16x32_bf16 v[86:89], v[10:13], v[26:29], v[86:89]
	global_load_lds_dwordx4 v126, s[90:91]
	s_add_i32 m0, s89, 0x2000
	v_mfma_f32_16x16x32_bf16 v[70:73], v[6:9], v[26:29], v[70:73]
	v_mfma_f32_16x16x32_bf16 v[54:57], v[2:5], v[26:29], v[54:57]
	global_load_lds_dwordx4 v128, s[90:91]
	s_add_i32 m0, s89, 0x4000
	v_mfma_f32_16x16x32_bf16 v[98:101], v[14:17], v[18:21], v[98:101]
	v_mfma_f32_16x16x32_bf16 v[82:85], v[10:13], v[18:21], v[82:85]
	global_load_lds_dwordx4 v130, s[92:93]
	v_mfma_f32_16x16x32_bf16 v[66:69], v[6:9], v[18:21], v[66:69]
	v_mfma_f32_16x16x32_bf16 v[50:53], v[2:5], v[18:21], v[50:53]
	s_add_u32 s90, s90, 64
	s_addc_u32 s91, s91, 0
	s_add_u32 s92, s92, 64
	s_addc_u32 s93, s93, 0
.LBB0_415:
	s_waitcnt lgkmcnt(0)
	s_barrier
	v_mfma_f32_16x16x32_bf16 v[90:93], v[14:17], v[106:109], v[90:93]
	v_mfma_f32_16x16x32_bf16 v[74:77], v[10:13], v[106:109], v[74:77]
	v_mfma_f32_16x16x32_bf16 v[58:61], v[6:9], v[106:109], v[58:61]
	v_mfma_f32_16x16x32_bf16 v[46:49], v[2:5], v[106:109], v[46:49]
	s_add_i32 s19, s8, -2
	s_and_b32 s29, s19, 3
	s_mulk_i32 s29, 0x6000
	v_add_u32_e32 v18, s29, v235
	ds_read_b128 v[118:121], v18
	ds_read_b128 v[114:117], v18 offset:1024
	ds_read_b128 v[110:113], v18 offset:2048
	ds_read_b128 v[106:109], v18 offset:3072
	v_add_u32_e32 v226, s29, v236
	ds_read_b128 v[26:29], v226
	ds_read_b128 v[18:21], v226 offset:1024
	v_mfma_f32_16x16x32_bf16 v[94:97], v[14:17], v[242:245], v[94:97]
	v_mfma_f32_16x16x32_bf16 v[78:81], v[10:13], v[242:245], v[78:81]
	v_mfma_f32_16x16x32_bf16 v[62:65], v[6:9], v[242:245], v[62:65]
	v_mfma_f32_16x16x32_bf16 v[42:45], v[2:5], v[242:245], v[42:45]
	s_mov_b64 s[26:27], -1
	s_and_b64 vcc, exec, s[24:25]
	s_cbranch_vccz .LBB0_417
	s_waitcnt vmcnt(0)
	s_mov_b64 s[26:27], 0

.LBB0_419:
	s_waitcnt lgkmcnt(0)
	s_barrier
	v_add_u32_e32 v198, s29, v237
	ds_read_b128 v[242:245], v198
	ds_read_b128 v[122:125], v198 offset:1024
	s_cmp_gt_u32 s17, 43
	s_cbranch_scc1 .Lgm_G2x_nodma1
	s_add_i32 s89, s28, s88
	s_mov_b32 m0, s89
	v_mfma_f32_16x16x32_bf16 v[102:105], v[118:121], v[26:29], v[102:105]
	v_mfma_f32_16x16x32_bf16 v[86:89], v[114:117], v[26:29], v[86:89]
	global_load_lds_dwordx4 v126, s[90:91]
	s_add_i32 m0, s89, 0x2000
	v_mfma_f32_16x16x32_bf16 v[70:73], v[110:113], v[26:29], v[70:73]
	v_mfma_f32_16x16x32_bf16 v[54:57], v[106:109], v[26:29], v[54:57]
	global_load_lds_dwordx4 v128, s[90:91]
	s_add_i32 m0, s89, 0x4000
	v_mfma_f32_16x16x32_bf16 v[98:101], v[118:121], v[18:21], v[98:101]
	v_mfma_f32_16x16x32_bf16 v[82:85], v[114:117], v[18:21], v[82:85]
	global_load_lds_dwordx4 v130, s[92:93]
	v_mfma_f32_16x16x32_bf16 v[66:69], v[110:113], v[18:21], v[66:69]
	v_mfma_f32_16x16x32_bf16 v[50:53], v[106:109], v[18:21], v[50:53]
	s_add_u32 s90, s90, 64
	s_addc_u32 s91, s91, 0
	s_add_u32 s92, s92, 64
	s_addc_u32 s93, s93, 0
.LBB0_421:
	s_waitcnt lgkmcnt(0)
	s_barrier
	v_mfma_f32_16x16x32_bf16 v[90:93], v[118:121], v[242:245], v[90:93]
	v_mfma_f32_16x16x32_bf16 v[74:77], v[114:117], v[242:245], v[74:77]
	v_mfma_f32_16x16x32_bf16 v[58:61], v[110:113], v[242:245], v[58:61]
	v_mfma_f32_16x16x32_bf16 v[46:49], v[106:109], v[242:245], v[46:49]
	s_andn2_b64 vcc, exec, s[22:23]
	s_cbranch_vccnz .LBB0_423
	s_add_i32 s22, s8, -1
	s_and_b32 s22, s22, 2
	s_mulk_i32 s22, 0x6000
	v_add_u32_e32 v18, s22, v235
	ds_read_b128 v[14:17], v18
	ds_read_b128 v[10:13], v18 offset:1024
	ds_read_b128 v[6:9], v18 offset:2048
	ds_read_b128 v[2:5], v18 offset:3072
	v_add_u32_e32 v198, s22, v236
	ds_read_b128 v[26:29], v198
	ds_read_b128 v[18:21], v198 offset:1024

.Lgm_G2x_nodma1:
	v_mfma_f32_16x16x32_bf16 v[102:105], v[118:121], v[26:29], v[102:105]
	v_mfma_f32_16x16x32_bf16 v[86:89], v[114:117], v[26:29], v[86:89]
	v_mfma_f32_16x16x32_bf16 v[70:73], v[110:113], v[26:29], v[70:73]
	v_mfma_f32_16x16x32_bf16 v[54:57], v[106:109], v[26:29], v[54:57]
	v_mfma_f32_16x16x32_bf16 v[98:101], v[118:121], v[18:21], v[98:101]
	v_mfma_f32_16x16x32_bf16 v[82:85], v[114:117], v[18:21], v[82:85]
	v_mfma_f32_16x16x32_bf16 v[66:69], v[110:113], v[18:21], v[66:69]
	v_mfma_f32_16x16x32_bf16 v[50:53], v[106:109], v[18:21], v[50:53]
	s_branch .LBB0_421
.Lgm_G2x_nodma0:
	v_mfma_f32_16x16x32_bf16 v[102:105], v[14:17], v[26:29], v[102:105]
	v_mfma_f32_16x16x32_bf16 v[86:89], v[10:13], v[26:29], v[86:89]
	v_mfma_f32_16x16x32_bf16 v[70:73], v[6:9], v[26:29], v[70:73]
	v_mfma_f32_16x16x32_bf16 v[54:57], v[2:5], v[26:29], v[54:57]
	v_mfma_f32_16x16x32_bf16 v[98:101], v[14:17], v[18:21], v[98:101]
	v_mfma_f32_16x16x32_bf16 v[82:85], v[10:13], v[18:21], v[82:85]
	v_mfma_f32_16x16x32_bf16 v[66:69], v[6:9], v[18:21], v[66:69]
	v_mfma_f32_16x16x32_bf16 v[50:53], v[2:5], v[18:21], v[50:53]
	s_branch .LBB0_415

.LBB0_649:
	s_waitcnt lgkmcnt(0)
	s_cmp_gt_u32 s30, 28
	s_cselect_b64 s[26:27], -1, 0
	s_and_b64 vcc, exec, s[26:27]
	s_barrier
	s_add_i32 s28, s31, 0xfffe8000
	s_and_b32 s34, s28, 0x10000
	v_add_u32_e32 v170, s34, v233
	ds_read_b128 v[162:165], v170
	ds_read_b128 v[166:169], v170 offset:1024
	ds_read_b128 v[234:237], v170 offset:2048
	ds_read_b128 v[238:241], v170 offset:3072
	s_cbranch_vccnz .Lgm_G1x_nodma0
	s_and_b32 s40, s31, 0x18000
	s_add_i32 s40, s40, s69
	s_mov_b32 m0, s40
	v_mfma_f32_16x16x32_bf16 v[126:129], v[130:133], v[158:161], v[126:129]
	v_mfma_f32_16x16x32_bf16 v[98:101], v[134:137], v[158:161], v[98:101]
	v_mfma_f32_16x16x32_bf16 v[66:69], v[138:141], v[158:161], v[66:69]
	global_load_lds_dwordx4 v188, s[94:95]
	s_add_i32 m0, s40, 0x2000
	v_mfma_f32_16x16x32_bf16 v[34:37], v[142:145], v[158:161], v[34:37]
	v_mfma_f32_16x16x32_bf16 v[122:125], v[130:133], v[154:157], v[122:125]
	v_mfma_f32_16x16x32_bf16 v[90:93], v[134:137], v[154:157], v[90:93]
	global_load_lds_dwordx4 v190, s[94:95]
	s_add_i32 m0, s40, 0x4000
	v_mfma_f32_16x16x32_bf16 v[58:61], v[138:141], v[154:157], v[58:61]
	v_mfma_f32_16x16x32_bf16 v[26:29], v[142:145], v[154:157], v[26:29]
	v_mfma_f32_16x16x32_bf16 v[118:121], v[130:133], v[150:153], v[118:121]
	global_load_lds_dwordx4 v192, s[42:43]
	s_add_i32 m0, s40, 0x6000
	v_mfma_f32_16x16x32_bf16 v[86:89], v[134:137], v[150:153], v[86:89]
	v_mfma_f32_16x16x32_bf16 v[54:57], v[138:141], v[150:153], v[54:57]
	v_mfma_f32_16x16x32_bf16 v[22:25], v[142:145], v[150:153], v[22:25]
	global_load_lds_dwordx4 v194, s[42:43]
	v_mfma_f32_16x16x32_bf16 v[114:117], v[130:133], v[146:149], v[114:117]
	v_mfma_f32_16x16x32_bf16 v[82:85], v[134:137], v[146:149], v[82:85]
	v_mfma_f32_16x16x32_bf16 v[50:53], v[138:141], v[146:149], v[50:53]
	v_mfma_f32_16x16x32_bf16 v[18:21], v[142:145], v[146:149], v[18:21]
	s_add_u32 s94, s94, 64
	s_addc_u32 s95, s95, 0
	s_add_u32 s42, s42, 64
	s_addc_u32 s43, s43, 0
.LBB0_651:
	s_waitcnt lgkmcnt(0)
	s_barrier
	v_mfma_f32_16x16x32_bf16 v[110:113], v[130:133], v[162:165], v[110:113]
	v_mfma_f32_16x16x32_bf16 v[78:81], v[134:137], v[162:165], v[78:81]
	v_mfma_f32_16x16x32_bf16 v[46:49], v[138:141], v[162:165], v[46:49]
	v_mfma_f32_16x16x32_bf16 v[14:17], v[142:145], v[162:165], v[14:17]
	v_mfma_f32_16x16x32_bf16 v[106:109], v[130:133], v[166:169], v[106:109]
	v_mfma_f32_16x16x32_bf16 v[74:77], v[134:137], v[166:169], v[74:77]
	v_mfma_f32_16x16x32_bf16 v[42:45], v[138:141], v[166:169], v[42:45]
	v_mfma_f32_16x16x32_bf16 v[10:13], v[142:145], v[166:169], v[10:13]
	s_add_i32 s28, s31, 0xffff0000
	s_and_b32 s35, s28, 0x18000
	v_add_u32_e32 v146, s35, v231
	ds_read_b128 v[174:177], v146
	ds_read_b128 v[170:173], v146 offset:1024
	ds_read_b128 v[166:169], v146 offset:2048
	ds_read_b128 v[162:165], v146 offset:3072
	v_add_u32_e32 v226, s35, v232
	ds_read_b128 v[158:161], v226
	ds_read_b128 v[154:157], v226 offset:1024
	ds_read_b128 v[150:153], v226 offset:2048
	ds_read_b128 v[146:149], v226 offset:3072
	v_mfma_f32_16x16x32_bf16 v[102:105], v[130:133], v[234:237], v[102:105]
	v_mfma_f32_16x16x32_bf16 v[70:73], v[134:137], v[234:237], v[70:73]
	v_mfma_f32_16x16x32_bf16 v[38:41], v[138:141], v[234:237], v[38:41]
	v_mfma_f32_16x16x32_bf16 v[6:9], v[142:145], v[234:237], v[6:9]
	v_mfma_f32_16x16x32_bf16 v[94:97], v[130:133], v[238:241], v[94:97]
	v_mfma_f32_16x16x32_bf16 v[62:65], v[134:137], v[238:241], v[62:65]
	v_mfma_f32_16x16x32_bf16 v[30:33], v[138:141], v[238:241], v[30:33]
	v_mfma_f32_16x16x32_bf16 v[2:5], v[142:145], v[238:241], v[2:5]
	s_mov_b64 s[28:29], -1
	s_and_b64 vcc, exec, s[26:27]
	s_cbranch_vccz .LBB0_653
	s_waitcnt vmcnt(0)
	s_mov_b64 s[28:29], 0

.LBB0_655:
	s_waitcnt lgkmcnt(0)
	s_barrier
	v_add_u32_e32 v226, s35, v233
	ds_read_b128 v[234:237], v226
	ds_read_b128 v[238:241], v226 offset:1024
	ds_read_b128 v[182:185], v226 offset:2048
	ds_read_b128 v[178:181], v226 offset:3072
	s_cmp_gt_u32 s30, 27
	s_cbranch_scc1 .Lgm_G1x_nodma1
	s_add_i32 s40, s34, s69
	s_mov_b32 m0, s40
	v_mfma_f32_16x16x32_bf16 v[126:129], v[174:177], v[158:161], v[126:129]
	v_mfma_f32_16x16x32_bf16 v[98:101], v[170:173], v[158:161], v[98:101]
	v_mfma_f32_16x16x32_bf16 v[66:69], v[166:169], v[158:161], v[66:69]
	global_load_lds_dwordx4 v188, s[94:95]
	s_add_i32 m0, s40, 0x2000
	v_mfma_f32_16x16x32_bf16 v[34:37], v[162:165], v[158:161], v[34:37]
	v_mfma_f32_16x16x32_bf16 v[122:125], v[174:177], v[154:157], v[122:125]
	v_mfma_f32_16x16x32_bf16 v[90:93], v[170:173], v[154:157], v[90:93]
	global_load_lds_dwordx4 v190, s[94:95]
	s_add_i32 m0, s40, 0x4000
	v_mfma_f32_16x16x32_bf16 v[58:61], v[166:169], v[154:157], v[58:61]
	v_mfma_f32_16x16x32_bf16 v[26:29], v[162:165], v[154:157], v[26:29]
	v_mfma_f32_16x16x32_bf16 v[118:121], v[174:177], v[150:153], v[118:121]
	global_load_lds_dwordx4 v192, s[42:43]
	s_add_i32 m0, s40, 0x6000
	v_mfma_f32_16x16x32_bf16 v[86:89], v[170:173], v[150:153], v[86:89]
	v_mfma_f32_16x16x32_bf16 v[54:57], v[166:169], v[150:153], v[54:57]
	v_mfma_f32_16x16x32_bf16 v[22:25], v[162:165], v[150:153], v[22:25]
	global_load_lds_dwordx4 v194, s[42:43]
	v_mfma_f32_16x16x32_bf16 v[114:117], v[174:177], v[146:149], v[114:117]
	v_mfma_f32_16x16x32_bf16 v[82:85], v[170:173], v[146:149], v[82:85]
	v_mfma_f32_16x16x32_bf16 v[50:53], v[166:169], v[146:149], v[50:53]
	v_mfma_f32_16x16x32_bf16 v[18:21], v[162:165], v[146:149], v[18:21]
	s_add_u32 s94, s94, 64
	s_addc_u32 s95, s95, 0
	s_add_u32 s42, s42, 64
	s_addc_u32 s43, s43, 0
.LBB0_657:
	s_waitcnt lgkmcnt(0)
	s_barrier
	v_mfma_f32_16x16x32_bf16 v[110:113], v[174:177], v[234:237], v[110:113]
	v_mfma_f32_16x16x32_bf16 v[78:81], v[170:173], v[234:237], v[78:81]
	v_mfma_f32_16x16x32_bf16 v[46:49], v[166:169], v[234:237], v[46:49]
	v_mfma_f32_16x16x32_bf16 v[14:17], v[162:165], v[234:237], v[14:17]
	v_mfma_f32_16x16x32_bf16 v[106:109], v[174:177], v[238:241], v[106:109]
	v_mfma_f32_16x16x32_bf16 v[74:77], v[170:173], v[238:241], v[74:77]
	v_mfma_f32_16x16x32_bf16 v[42:45], v[166:169], v[238:241], v[42:45]
	v_mfma_f32_16x16x32_bf16 v[10:13], v[162:165], v[238:241], v[10:13]
	s_andn2_b64 vcc, exec, s[24:25]
	s_cbranch_vccnz .LBB0_644
	s_add_i32 s24, s31, 0xffff8000
	s_and_b32 s24, s24, 0x10000
	v_add_u32_e32 v146, s24, v231
	ds_read_b128 v[130:133], v146
	ds_read_b128 v[134:137], v146 offset:1024
	ds_read_b128 v[138:141], v146 offset:2048
	ds_read_b128 v[142:145], v146 offset:3072
	v_add_u32_e32 v226, s24, v232
	ds_read_b128 v[158:161], v226
	ds_read_b128 v[154:157], v226 offset:1024
	ds_read_b128 v[150:153], v226 offset:2048
	ds_read_b128 v[146:149], v226 offset:3072
	s_branch .LBB0_644
.Lgm_G1x_nodma1:
	v_mfma_f32_16x16x32_bf16 v[126:129], v[174:177], v[158:161], v[126:129]
	v_mfma_f32_16x16x32_bf16 v[98:101], v[170:173], v[158:161], v[98:101]
	v_mfma_f32_16x16x32_bf16 v[66:69], v[166:169], v[158:161], v[66:69]
	v_mfma_f32_16x16x32_bf16 v[34:37], v[162:165], v[158:161], v[34:37]
	v_mfma_f32_16x16x32_bf16 v[122:125], v[174:177], v[154:157], v[122:125]
	v_mfma_f32_16x16x32_bf16 v[90:93], v[170:173], v[154:157], v[90:93]
	v_mfma_f32_16x16x32_bf16 v[58:61], v[166:169], v[154:157], v[58:61]
	v_mfma_f32_16x16x32_bf16 v[26:29], v[162:165], v[154:157], v[26:29]
	v_mfma_f32_16x16x32_bf16 v[118:121], v[174:177], v[150:153], v[118:121]
	v_mfma_f32_16x16x32_bf16 v[86:89], v[170:173], v[150:153], v[86:89]
	v_mfma_f32_16x16x32_bf16 v[54:57], v[166:169], v[150:153], v[54:57]
	v_mfma_f32_16x16x32_bf16 v[22:25], v[162:165], v[150:153], v[22:25]
	v_mfma_f32_16x16x32_bf16 v[114:117], v[174:177], v[146:149], v[114:117]
	v_mfma_f32_16x16x32_bf16 v[82:85], v[170:173], v[146:149], v[82:85]
	v_mfma_f32_16x16x32_bf16 v[50:53], v[166:169], v[146:149], v[50:53]
	v_mfma_f32_16x16x32_bf16 v[18:21], v[162:165], v[146:149], v[18:21]
	s_branch .LBB0_657
.Lgm_G1x_nodma0:
	v_mfma_f32_16x16x32_bf16 v[126:129], v[130:133], v[158:161], v[126:129]
	v_mfma_f32_16x16x32_bf16 v[98:101], v[134:137], v[158:161], v[98:101]
	v_mfma_f32_16x16x32_bf16 v[66:69], v[138:141], v[158:161], v[66:69]
	v_mfma_f32_16x16x32_bf16 v[34:37], v[142:145], v[158:161], v[34:37]
	v_mfma_f32_16x16x32_bf16 v[122:125], v[130:133], v[154:157], v[122:125]
	v_mfma_f32_16x16x32_bf16 v[90:93], v[134:137], v[154:157], v[90:93]
	v_mfma_f32_16x16x32_bf16 v[58:61], v[138:141], v[154:157], v[58:61]
	v_mfma_f32_16x16x32_bf16 v[26:29], v[142:145], v[154:157], v[26:29]
	v_mfma_f32_16x16x32_bf16 v[118:121], v[130:133], v[150:153], v[118:121]
	v_mfma_f32_16x16x32_bf16 v[86:89], v[134:137], v[150:153], v[86:89]
	v_mfma_f32_16x16x32_bf16 v[54:57], v[138:141], v[150:153], v[54:57]
	v_mfma_f32_16x16x32_bf16 v[22:25], v[142:145], v[150:153], v[22:25]
	v_mfma_f32_16x16x32_bf16 v[114:117], v[130:133], v[146:149], v[114:117]
	v_mfma_f32_16x16x32_bf16 v[82:85], v[134:137], v[146:149], v[82:85]
	v_mfma_f32_16x16x32_bf16 v[50:53], v[138:141], v[146:149], v[50:53]
	v_mfma_f32_16x16x32_bf16 v[18:21], v[142:145], v[146:149], v[18:21]
	s_branch .LBB0_651
